# down-proj EpiRes epilogue rewritten half-major with all row loads in flight (counted vmcnt) + split-K consumer slab adds as a 16-deep pre-pass
# speedup vs baseline: 1.0331x; 1.0261x over previous
.LBB0_321:
	s_ashr_i32 s51, s50, 31
	s_lshl_b64 s[0:1], s[50:51], 18
	v_readlane_b32 s10, v254, 21
	v_readlane_b32 s11, v254, 22
	s_add_u32 s0, s10, s0
	s_addc_u32 s1, s11, s1
	v_lshl_or_b32 v216, s8, 8, v243
	s_lshl_b32 s8, s4, 8
	s_add_i32 s10, s8, 0xfffff000
	s_lshr_b32 s10, s10, 11
	s_mulk_i32 s10, 0x1800
	s_addk_i32 s10, 0x1800
	s_cmp_gt_i32 s4, 15
	s_cselect_b32 s86, s10, 0
	s_lshl_b64 s[10:11], s[86:87], 2
	s_add_u32 s10, s38, s10
	v_readlane_b32 s4, v254, 26
	s_addc_u32 s11, s4, s11
	s_andn2_b64 vcc, exec, s[14:15]
	s_cbranch_vccnz .Ldn_noadd
	v_lshl_add_u64 v[214:215], s[0:1], 0, v[206:207]
	s_mov_b64 s[0:1], 0x2000
	global_load_dwordx4 v[130:133], v[214:215], off
	v_lshl_add_u64 v[214:215], v[214:215], 0, s[0:1]
	global_load_dwordx4 v[134:137], v[214:215], off
	v_lshl_add_u64 v[214:215], v[214:215], 0, s[0:1]
	global_load_dwordx4 v[138:141], v[214:215], off
	v_lshl_add_u64 v[214:215], v[214:215], 0, s[0:1]
	global_load_dwordx4 v[142:145], v[214:215], off
	v_lshl_add_u64 v[214:215], v[214:215], 0, s[0:1]
	global_load_dwordx4 v[146:149], v[214:215], off
	v_lshl_add_u64 v[214:215], v[214:215], 0, s[0:1]
	global_load_dwordx4 v[150:153], v[214:215], off
	v_lshl_add_u64 v[214:215], v[214:215], 0, s[0:1]
	global_load_dwordx4 v[154:157], v[214:215], off
	v_lshl_add_u64 v[214:215], v[214:215], 0, s[0:1]
	global_load_dwordx4 v[158:161], v[214:215], off
	v_lshl_add_u64 v[214:215], v[214:215], 0, s[0:1]
	global_load_dwordx4 v[162:165], v[214:215], off
	v_lshl_add_u64 v[214:215], v[214:215], 0, s[0:1]
	global_load_dwordx4 v[166:169], v[214:215], off
	v_lshl_add_u64 v[214:215], v[214:215], 0, s[0:1]
	global_load_dwordx4 v[170:173], v[214:215], off
	v_lshl_add_u64 v[214:215], v[214:215], 0, s[0:1]
	global_load_dwordx4 v[174:177], v[214:215], off
	v_lshl_add_u64 v[214:215], v[214:215], 0, s[0:1]
	global_load_dwordx4 v[178:181], v[214:215], off
	v_lshl_add_u64 v[214:215], v[214:215], 0, s[0:1]
	global_load_dwordx4 v[182:185], v[214:215], off
	v_lshl_add_u64 v[214:215], v[214:215], 0, s[0:1]
	global_load_dwordx4 v[186:189], v[214:215], off
	v_lshl_add_u64 v[214:215], v[214:215], 0, s[0:1]
	global_load_dwordx4 v[194:197], v[214:215], off
	v_lshl_add_u64 v[214:215], v[214:215], 0, s[0:1]
	s_waitcnt vmcnt(15)
	v_pk_add_f32 v[126:127], v[126:127], v[130:131]
	v_pk_add_f32 v[128:129], v[128:129], v[132:133]
	global_load_dwordx4 v[130:133], v[214:215], off
	v_lshl_add_u64 v[214:215], v[214:215], 0, s[0:1]
	s_waitcnt vmcnt(15)
	v_pk_add_f32 v[122:123], v[122:123], v[134:135]
	v_pk_add_f32 v[124:125], v[124:125], v[136:137]
	global_load_dwordx4 v[134:137], v[214:215], off
	v_lshl_add_u64 v[214:215], v[214:215], 0, s[0:1]
	s_waitcnt vmcnt(15)
	v_pk_add_f32 v[118:119], v[118:119], v[138:139]
	v_pk_add_f32 v[120:121], v[120:121], v[140:141]
	global_load_dwordx4 v[138:141], v[214:215], off
	v_lshl_add_u64 v[214:215], v[214:215], 0, s[0:1]
	s_waitcnt vmcnt(15)
	v_pk_add_f32 v[114:115], v[114:115], v[142:143]
	v_pk_add_f32 v[116:117], v[116:117], v[144:145]
	global_load_dwordx4 v[142:145], v[214:215], off
	v_lshl_add_u64 v[214:215], v[214:215], 0, s[0:1]
	s_waitcnt vmcnt(15)
	v_pk_add_f32 v[110:111], v[110:111], v[146:147]
	v_pk_add_f32 v[112:113], v[112:113], v[148:149]
	global_load_dwordx4 v[146:149], v[214:215], off
	v_lshl_add_u64 v[214:215], v[214:215], 0, s[0:1]
	s_waitcnt vmcnt(15)
	v_pk_add_f32 v[106:107], v[106:107], v[150:151]
	v_pk_add_f32 v[108:109], v[108:109], v[152:153]
	global_load_dwordx4 v[150:153], v[214:215], off
	v_lshl_add_u64 v[214:215], v[214:215], 0, s[0:1]
	s_waitcnt vmcnt(15)
	v_pk_add_f32 v[102:103], v[102:103], v[154:155]
	v_pk_add_f32 v[104:105], v[104:105], v[156:157]
	global_load_dwordx4 v[154:157], v[214:215], off
	v_lshl_add_u64 v[214:215], v[214:215], 0, s[0:1]
	s_waitcnt vmcnt(15)
	v_pk_add_f32 v[98:99], v[98:99], v[158:159]
	v_pk_add_f32 v[100:101], v[100:101], v[160:161]
	global_load_dwordx4 v[158:161], v[214:215], off
	v_lshl_add_u64 v[214:215], v[214:215], 0, s[0:1]
	s_waitcnt vmcnt(15)
	v_pk_add_f32 v[94:95], v[94:95], v[162:163]
	v_pk_add_f32 v[96:97], v[96:97], v[164:165]
	global_load_dwordx4 v[162:165], v[214:215], off
	v_lshl_add_u64 v[214:215], v[214:215], 0, s[0:1]
	s_waitcnt vmcnt(15)
	v_pk_add_f32 v[90:91], v[90:91], v[166:167]
	v_pk_add_f32 v[92:93], v[92:93], v[168:169]
	global_load_dwordx4 v[166:169], v[214:215], off
	v_lshl_add_u64 v[214:215], v[214:215], 0, s[0:1]
	s_waitcnt vmcnt(15)
	v_pk_add_f32 v[86:87], v[86:87], v[170:171]
	v_pk_add_f32 v[88:89], v[88:89], v[172:173]
	global_load_dwordx4 v[170:173], v[214:215], off
	v_lshl_add_u64 v[214:215], v[214:215], 0, s[0:1]
	s_waitcnt vmcnt(15)
	v_pk_add_f32 v[82:83], v[82:83], v[174:175]
	v_pk_add_f32 v[84:85], v[84:85], v[176:177]
	global_load_dwordx4 v[174:177], v[214:215], off
	v_lshl_add_u64 v[214:215], v[214:215], 0, s[0:1]
	s_waitcnt vmcnt(15)
	v_pk_add_f32 v[78:79], v[78:79], v[178:179]
	v_pk_add_f32 v[80:81], v[80:81], v[180:181]
	global_load_dwordx4 v[178:181], v[214:215], off
	v_lshl_add_u64 v[214:215], v[214:215], 0, s[0:1]
	s_waitcnt vmcnt(15)
	v_pk_add_f32 v[74:75], v[74:75], v[182:183]
	v_pk_add_f32 v[76:77], v[76:77], v[184:185]
	global_load_dwordx4 v[182:185], v[214:215], off
	v_lshl_add_u64 v[214:215], v[214:215], 0, s[0:1]
	s_waitcnt vmcnt(15)
	v_pk_add_f32 v[70:71], v[70:71], v[186:187]
	v_pk_add_f32 v[72:73], v[72:73], v[188:189]
	global_load_dwordx4 v[186:189], v[214:215], off
	v_lshl_add_u64 v[214:215], v[214:215], 0, s[0:1]
	s_waitcnt vmcnt(15)
	v_pk_add_f32 v[66:67], v[66:67], v[194:195]
	v_pk_add_f32 v[68:69], v[68:69], v[196:197]
	global_load_dwordx4 v[194:197], v[214:215], off
	s_waitcnt vmcnt(15)
	v_pk_add_f32 v[62:63], v[62:63], v[130:131]
	v_pk_add_f32 v[64:65], v[64:65], v[132:133]
	s_waitcnt vmcnt(14)
	v_pk_add_f32 v[58:59], v[58:59], v[134:135]
	v_pk_add_f32 v[60:61], v[60:61], v[136:137]
	s_waitcnt vmcnt(13)
	v_pk_add_f32 v[54:55], v[54:55], v[138:139]
	v_pk_add_f32 v[56:57], v[56:57], v[140:141]
	s_waitcnt vmcnt(12)
	v_pk_add_f32 v[50:51], v[50:51], v[142:143]
	v_pk_add_f32 v[52:53], v[52:53], v[144:145]
	s_waitcnt vmcnt(11)
	v_pk_add_f32 v[46:47], v[46:47], v[146:147]
	v_pk_add_f32 v[48:49], v[48:49], v[148:149]
	s_waitcnt vmcnt(10)
	v_pk_add_f32 v[42:43], v[42:43], v[150:151]
	v_pk_add_f32 v[44:45], v[44:45], v[152:153]
	s_waitcnt vmcnt(9)
	v_pk_add_f32 v[38:39], v[38:39], v[154:155]
	v_pk_add_f32 v[40:41], v[40:41], v[156:157]
	s_waitcnt vmcnt(8)
	v_pk_add_f32 v[34:35], v[34:35], v[158:159]
	v_pk_add_f32 v[36:37], v[36:37], v[160:161]
	s_waitcnt vmcnt(7)
	v_pk_add_f32 v[30:31], v[30:31], v[162:163]
	v_pk_add_f32 v[32:33], v[32:33], v[164:165]
	s_waitcnt vmcnt(6)
	v_pk_add_f32 v[26:27], v[26:27], v[166:167]
	v_pk_add_f32 v[28:29], v[28:29], v[168:169]
	s_waitcnt vmcnt(5)
	v_pk_add_f32 v[22:23], v[22:23], v[170:171]
	v_pk_add_f32 v[24:25], v[24:25], v[172:173]
	s_waitcnt vmcnt(4)
	v_pk_add_f32 v[18:19], v[18:19], v[174:175]
	v_pk_add_f32 v[20:21], v[20:21], v[176:177]
	s_waitcnt vmcnt(3)
	v_pk_add_f32 v[14:15], v[14:15], v[178:179]
	v_pk_add_f32 v[16:17], v[16:17], v[180:181]
	s_waitcnt vmcnt(2)
	v_pk_add_f32 v[10:11], v[10:11], v[182:183]
	v_pk_add_f32 v[12:13], v[12:13], v[184:185]
	s_waitcnt vmcnt(1)
	v_pk_add_f32 v[6:7], v[6:7], v[186:187]
	v_pk_add_f32 v[8:9], v[8:9], v[188:189]
	s_waitcnt vmcnt(0)
	v_pk_add_f32 v[2:3], v[2:3], v[194:195]
	v_pk_add_f32 v[4:5], v[4:5], v[196:197]
.Ldn_noadd:
	v_ashrrev_i32_e32 v217, 31, v216
	v_lshlrev_b64 v[152:153], 2, v[216:217]
	v_lshl_add_u64 v[220:221], s[48:49], 0, v[152:153]
	v_lshl_add_u64 v[222:223], s[46:47], 0, v[152:153]
	v_lshl_add_u64 v[218:219], s[10:11], 0, v[152:153]
	global_load_dwordx4 v[154:157], v[220:221], off offset:16
	global_load_dwordx4 v[166:169], v[220:221], off
	global_load_dwordx4 v[162:165], v[222:223], off offset:16
	global_load_dwordx4 v[170:173], v[222:223], off
	global_load_dwordx4 v[158:161], v[218:219], off offset:16
	global_load_dwordx4 v[174:177], v[218:219], off
	v_add_u32_e32 v218, s8, v201
	v_ashrrev_i32_e32 v219, 31, v218
	v_lshlrev_b64 v[220:221], 11, v[218:219]
	v_lshl_add_u64 v[220:221], s[12:13], 0, v[220:221]
	v_lshl_add_u64 v[214:215], v[218:219], 3, s[6:7]
	v_lshl_add_u64 v[216:217], v[216:217], 1, v[220:221]
	v_mov_b64_e32 v[218:219], v[216:217]
	global_load_dwordx2 v[194:195], v[214:215], off
	global_load_dwordx4 v[178:181], v[216:217], off
	s_mov_b32 s0, 0x8000
	s_mov_b32 s1, 0
	v_lshl_add_u64 v[216:217], v[216:217], 0, s[0:1]
	global_load_dwordx2 v[196:197], v[214:215], off offset:128
	global_load_dwordx4 v[182:185], v[216:217], off
	v_lshl_add_u64 v[216:217], v[216:217], 0, s[0:1]
	global_load_dwordx2 v[232:233], v[214:215], off offset:256
	global_load_dwordx4 v[186:189], v[216:217], off
	v_lshl_add_u64 v[216:217], v[216:217], 0, s[0:1]
	global_load_dwordx2 v[248:249], v[214:215], off offset:384
	global_load_dwordx4 v[130:133], v[216:217], off
	s_mov_b32 s0, 0x28000
	s_mov_b32 s1, 0
	v_lshl_add_u64 v[216:217], v[216:217], 0, s[0:1]
	global_load_dwordx2 v[146:147], v[214:215], off offset:1024
	global_load_dwordx4 v[134:137], v[216:217], off
	s_mov_b32 s0, 0x8000
	s_mov_b32 s1, 0
	v_lshl_add_u64 v[216:217], v[216:217], 0, s[0:1]
	global_load_dwordx2 v[148:149], v[214:215], off offset:1152
	global_load_dwordx4 v[138:141], v[216:217], off
	v_lshl_add_u64 v[216:217], v[216:217], 0, s[0:1]
	global_load_dwordx2 v[150:151], v[214:215], off offset:1280
	global_load_dwordx4 v[142:145], v[216:217], off
	v_lshl_add_u64 v[216:217], v[216:217], 0, s[0:1]
	s_waitcnt vmcnt(12)
	v_lshlrev_b32_e32 v220, 16, v178
	v_and_b32_e32 v221, 0xffff0000, v178
	v_lshlrev_b32_e32 v178, 16, v179
	v_and_b32_e32 v179, 0xffff0000, v179
	v_lshlrev_b32_e32 v222, 16, v180
	v_and_b32_e32 v223, 0xffff0000, v180
	v_lshlrev_b32_e32 v180, 16, v181
	v_and_b32_e32 v181, 0xffff0000, v181
	v_sub_f32_e32 v221, v221, v194
	v_sub_f32_e32 v220, v220, v194
	v_sub_f32_e32 v179, v179, v194
	v_sub_f32_e32 v178, v178, v194
	v_pk_mul_f32 v[178:179], v[194:195], v[178:179] op_sel:[1,0]
	v_pk_mul_f32 v[220:221], v[194:195], v[220:221] op_sel:[1,0]
	v_sub_f32_e32 v223, v223, v194
	v_sub_f32_e32 v222, v222, v194
	v_sub_f32_e32 v181, v181, v194
	v_sub_f32_e32 v180, v180, v194
	v_pk_fma_f32 v[220:221], v[166:167], v[220:221], v[170:171]
	v_pk_fma_f32 v[178:179], v[168:169], v[178:179], v[172:173]
	v_pk_mul_f32 v[180:181], v[194:195], v[180:181] op_sel:[1,0]
	v_pk_mul_f32 v[222:223], v[194:195], v[222:223] op_sel:[1,0]
	v_pk_mul_f32 v[128:129], v[176:177], v[128:129]
	v_pk_mul_f32 v[126:127], v[174:175], v[126:127]
	v_pk_fma_f32 v[222:223], v[154:155], v[222:223], v[162:163]
	v_pk_fma_f32 v[180:181], v[156:157], v[180:181], v[164:165]
	v_pk_fma_f32 v[128:129], v[178:179], s[56:57], v[128:129] op_sel_hi:[1,0,1]
	v_pk_fma_f32 v[126:127], v[220:221], s[56:57], v[126:127] op_sel_hi:[1,0,1]
	v_pk_mul_f32 v[124:125], v[160:161], v[124:125]
	v_pk_mul_f32 v[122:123], v[158:159], v[122:123]
	v_pk_fma_f32 v[124:125], v[180:181], s[56:57], v[124:125] op_sel_hi:[1,0,1]
	v_pk_fma_f32 v[122:123], v[222:223], s[56:57], v[122:123] op_sel_hi:[1,0,1]
	v_cvt_pk_bf16_f32 v126, v126, v127
	v_cvt_pk_bf16_f32 v127, v128, v129
	v_cvt_pk_bf16_f32 v128, v122, v123
	v_cvt_pk_bf16_f32 v129, v124, v125
	global_store_dwordx4 v[218:219], v[126:129], off
	global_load_dwordx2 v[194:195], v[214:215], off
	global_load_dwordx4 v[178:181], v[218:219], off offset:256
	v_lshl_add_u64 v[220:221], s[10:11], 0, v[152:153]
	s_nop 1
	global_load_dwordx4 v[126:129], v[220:221], off offset:512
	global_load_dwordx4 v[122:125], v[220:221], off offset:528
	v_lshl_add_u64 v[218:219], v[218:219], 0, s[0:1]
	s_waitcnt vmcnt(15)
	v_lshlrev_b32_e32 v220, 16, v182
	v_and_b32_e32 v221, 0xffff0000, v182
	v_lshlrev_b32_e32 v182, 16, v183
	v_and_b32_e32 v183, 0xffff0000, v183
	v_lshlrev_b32_e32 v222, 16, v184
	v_and_b32_e32 v223, 0xffff0000, v184
	v_lshlrev_b32_e32 v184, 16, v185
	v_and_b32_e32 v185, 0xffff0000, v185
	v_sub_f32_e32 v221, v221, v196
	v_sub_f32_e32 v220, v220, v196
	v_sub_f32_e32 v183, v183, v196
	v_sub_f32_e32 v182, v182, v196
	v_pk_mul_f32 v[182:183], v[196:197], v[182:183] op_sel:[1,0]
	v_pk_mul_f32 v[220:221], v[196:197], v[220:221] op_sel:[1,0]
	v_sub_f32_e32 v223, v223, v196
	v_sub_f32_e32 v222, v222, v196
	v_sub_f32_e32 v185, v185, v196
	v_sub_f32_e32 v184, v184, v196
	v_pk_fma_f32 v[220:221], v[166:167], v[220:221], v[170:171]
	v_pk_fma_f32 v[182:183], v[168:169], v[182:183], v[172:173]
	v_pk_mul_f32 v[184:185], v[196:197], v[184:185] op_sel:[1,0]
	v_pk_mul_f32 v[222:223], v[196:197], v[222:223] op_sel:[1,0]
	v_pk_mul_f32 v[120:121], v[176:177], v[120:121]
	v_pk_mul_f32 v[118:119], v[174:175], v[118:119]
	v_pk_fma_f32 v[222:223], v[154:155], v[222:223], v[162:163]
	v_pk_fma_f32 v[184:185], v[156:157], v[184:185], v[164:165]
	v_pk_fma_f32 v[120:121], v[182:183], s[56:57], v[120:121] op_sel_hi:[1,0,1]
	v_pk_fma_f32 v[118:119], v[220:221], s[56:57], v[118:119] op_sel_hi:[1,0,1]
	v_pk_mul_f32 v[116:117], v[160:161], v[116:117]
	v_pk_mul_f32 v[114:115], v[158:159], v[114:115]
	v_pk_fma_f32 v[116:117], v[184:185], s[56:57], v[116:117] op_sel_hi:[1,0,1]
	v_pk_fma_f32 v[114:115], v[222:223], s[56:57], v[114:115] op_sel_hi:[1,0,1]
	v_cvt_pk_bf16_f32 v118, v118, v119
	v_cvt_pk_bf16_f32 v119, v120, v121
	v_cvt_pk_bf16_f32 v120, v114, v115
	v_cvt_pk_bf16_f32 v121, v116, v117
	global_store_dwordx4 v[218:219], v[118:121], off
	global_load_dwordx2 v[196:197], v[214:215], off offset:128
	global_load_dwordx4 v[182:185], v[218:219], off offset:256
	v_lshl_add_u64 v[220:221], s[48:49], 0, v[152:153]
	s_nop 1
	global_load_dwordx4 v[118:121], v[220:221], off offset:512
	global_load_dwordx4 v[114:117], v[220:221], off offset:528
	v_lshl_add_u64 v[218:219], v[218:219], 0, s[0:1]
	s_waitcnt vmcnt(18)
	v_lshlrev_b32_e32 v220, 16, v186
	v_and_b32_e32 v221, 0xffff0000, v186
	v_lshlrev_b32_e32 v186, 16, v187
	v_and_b32_e32 v187, 0xffff0000, v187
	v_lshlrev_b32_e32 v222, 16, v188
	v_and_b32_e32 v223, 0xffff0000, v188
	v_lshlrev_b32_e32 v188, 16, v189
	v_and_b32_e32 v189, 0xffff0000, v189
	v_sub_f32_e32 v221, v221, v232
	v_sub_f32_e32 v220, v220, v232
	v_sub_f32_e32 v187, v187, v232
	v_sub_f32_e32 v186, v186, v232
	v_pk_mul_f32 v[186:187], v[232:233], v[186:187] op_sel:[1,0]
	v_pk_mul_f32 v[220:221], v[232:233], v[220:221] op_sel:[1,0]
	v_sub_f32_e32 v223, v223, v232
	v_sub_f32_e32 v222, v222, v232
	v_sub_f32_e32 v189, v189, v232
	v_sub_f32_e32 v188, v188, v232
	v_pk_fma_f32 v[220:221], v[166:167], v[220:221], v[170:171]
	v_pk_fma_f32 v[186:187], v[168:169], v[186:187], v[172:173]
	v_pk_mul_f32 v[188:189], v[232:233], v[188:189] op_sel:[1,0]
	v_pk_mul_f32 v[222:223], v[232:233], v[222:223] op_sel:[1,0]
	v_pk_mul_f32 v[112:113], v[176:177], v[112:113]
	v_pk_mul_f32 v[110:111], v[174:175], v[110:111]
	v_pk_fma_f32 v[222:223], v[154:155], v[222:223], v[162:163]
	v_pk_fma_f32 v[188:189], v[156:157], v[188:189], v[164:165]
	v_pk_fma_f32 v[112:113], v[186:187], s[56:57], v[112:113] op_sel_hi:[1,0,1]
	v_pk_fma_f32 v[110:111], v[220:221], s[56:57], v[110:111] op_sel_hi:[1,0,1]
	v_pk_mul_f32 v[108:109], v[160:161], v[108:109]
	v_pk_mul_f32 v[106:107], v[158:159], v[106:107]
	v_pk_fma_f32 v[108:109], v[188:189], s[56:57], v[108:109] op_sel_hi:[1,0,1]
	v_pk_fma_f32 v[106:107], v[222:223], s[56:57], v[106:107] op_sel_hi:[1,0,1]
	v_cvt_pk_bf16_f32 v110, v110, v111
	v_cvt_pk_bf16_f32 v111, v112, v113
	v_cvt_pk_bf16_f32 v112, v106, v107
	v_cvt_pk_bf16_f32 v113, v108, v109
	global_store_dwordx4 v[218:219], v[110:113], off
	global_load_dwordx2 v[232:233], v[214:215], off offset:256
	global_load_dwordx4 v[186:189], v[218:219], off offset:256
	v_lshl_add_u64 v[220:221], s[46:47], 0, v[152:153]
	s_nop 1
	global_load_dwordx4 v[110:113], v[220:221], off offset:512
	global_load_dwordx4 v[106:109], v[220:221], off offset:528
	v_lshl_add_u64 v[218:219], v[218:219], 0, s[0:1]
	s_waitcnt vmcnt(21)
	v_lshlrev_b32_e32 v220, 16, v130
	v_and_b32_e32 v221, 0xffff0000, v130
	v_lshlrev_b32_e32 v130, 16, v131
	v_and_b32_e32 v131, 0xffff0000, v131
	v_lshlrev_b32_e32 v222, 16, v132
	v_and_b32_e32 v223, 0xffff0000, v132
	v_lshlrev_b32_e32 v132, 16, v133
	v_and_b32_e32 v133, 0xffff0000, v133
	v_sub_f32_e32 v221, v221, v248
	v_sub_f32_e32 v220, v220, v248
	v_sub_f32_e32 v131, v131, v248
	v_sub_f32_e32 v130, v130, v248
	v_pk_mul_f32 v[130:131], v[248:249], v[130:131] op_sel:[1,0]
	v_pk_mul_f32 v[220:221], v[248:249], v[220:221] op_sel:[1,0]
	v_sub_f32_e32 v223, v223, v248
	v_sub_f32_e32 v222, v222, v248
	v_sub_f32_e32 v133, v133, v248
	v_sub_f32_e32 v132, v132, v248
	v_pk_fma_f32 v[220:221], v[166:167], v[220:221], v[170:171]
	v_pk_fma_f32 v[130:131], v[168:169], v[130:131], v[172:173]
	v_pk_mul_f32 v[132:133], v[248:249], v[132:133] op_sel:[1,0]
	v_pk_mul_f32 v[222:223], v[248:249], v[222:223] op_sel:[1,0]
	v_pk_mul_f32 v[104:105], v[176:177], v[104:105]
	v_pk_mul_f32 v[102:103], v[174:175], v[102:103]
	v_pk_fma_f32 v[222:223], v[154:155], v[222:223], v[162:163]
	v_pk_fma_f32 v[132:133], v[156:157], v[132:133], v[164:165]
	v_pk_fma_f32 v[104:105], v[130:131], s[56:57], v[104:105] op_sel_hi:[1,0,1]
	v_pk_fma_f32 v[102:103], v[220:221], s[56:57], v[102:103] op_sel_hi:[1,0,1]
	v_pk_mul_f32 v[100:101], v[160:161], v[100:101]
	v_pk_mul_f32 v[98:99], v[158:159], v[98:99]
	v_pk_fma_f32 v[100:101], v[132:133], s[56:57], v[100:101] op_sel_hi:[1,0,1]
	v_pk_fma_f32 v[98:99], v[222:223], s[56:57], v[98:99] op_sel_hi:[1,0,1]
	v_cvt_pk_bf16_f32 v102, v102, v103
	v_cvt_pk_bf16_f32 v103, v104, v105
	v_cvt_pk_bf16_f32 v104, v98, v99
	v_cvt_pk_bf16_f32 v105, v100, v101
	global_store_dwordx4 v[218:219], v[102:105], off
	s_nop 0
	global_load_dwordx2 v[102:103], v[214:215], off offset:384
	global_load_dwordx4 v[98:101], v[218:219], off offset:256
	global_load_dwordx2 v[248:249], v[214:215], off offset:1408
	global_load_dwordx4 v[130:133], v[216:217], off
	s_mov_b32 s0, 0x28000
	s_mov_b32 s1, 0
	v_lshl_add_u64 v[218:219], v[218:219], 0, s[0:1]
	s_waitcnt vmcnt(24)
	v_lshlrev_b32_e32 v220, 16, v134
	v_and_b32_e32 v221, 0xffff0000, v134
	v_lshlrev_b32_e32 v134, 16, v135
	v_and_b32_e32 v135, 0xffff0000, v135
	v_lshlrev_b32_e32 v222, 16, v136
	v_and_b32_e32 v223, 0xffff0000, v136
	v_lshlrev_b32_e32 v136, 16, v137
	v_and_b32_e32 v137, 0xffff0000, v137
	v_sub_f32_e32 v221, v221, v146
	v_sub_f32_e32 v220, v220, v146
	v_sub_f32_e32 v135, v135, v146
	v_sub_f32_e32 v134, v134, v146
	v_pk_mul_f32 v[134:135], v[146:147], v[134:135] op_sel:[1,0]
	v_pk_mul_f32 v[220:221], v[146:147], v[220:221] op_sel:[1,0]
	v_sub_f32_e32 v223, v223, v146
	v_sub_f32_e32 v222, v222, v146
	v_sub_f32_e32 v137, v137, v146
	v_sub_f32_e32 v136, v136, v146
	v_pk_fma_f32 v[220:221], v[166:167], v[220:221], v[170:171]
	v_pk_fma_f32 v[134:135], v[168:169], v[134:135], v[172:173]
	v_pk_mul_f32 v[136:137], v[146:147], v[136:137] op_sel:[1,0]
	v_pk_mul_f32 v[222:223], v[146:147], v[222:223] op_sel:[1,0]
	v_pk_mul_f32 v[64:65], v[176:177], v[64:65]
	v_pk_mul_f32 v[62:63], v[174:175], v[62:63]
	v_pk_fma_f32 v[222:223], v[154:155], v[222:223], v[162:163]
	v_pk_fma_f32 v[136:137], v[156:157], v[136:137], v[164:165]
	v_pk_fma_f32 v[64:65], v[134:135], s[56:57], v[64:65] op_sel_hi:[1,0,1]
	v_pk_fma_f32 v[62:63], v[220:221], s[56:57], v[62:63] op_sel_hi:[1,0,1]
	v_pk_mul_f32 v[60:61], v[160:161], v[60:61]
	v_pk_mul_f32 v[58:59], v[158:159], v[58:59]
	v_pk_fma_f32 v[60:61], v[136:137], s[56:57], v[60:61] op_sel_hi:[1,0,1]
	v_pk_fma_f32 v[58:59], v[222:223], s[56:57], v[58:59] op_sel_hi:[1,0,1]
	v_cvt_pk_bf16_f32 v62, v62, v63
	v_cvt_pk_bf16_f32 v63, v64, v65
	v_cvt_pk_bf16_f32 v64, v58, v59
	v_cvt_pk_bf16_f32 v65, v60, v61
	global_store_dwordx4 v[218:219], v[62:65], off
	s_nop 0
	global_load_dwordx2 v[62:63], v[214:215], off offset:1024
	global_load_dwordx4 v[58:61], v[218:219], off offset:256
	s_mov_b32 s0, 0x8000
	s_mov_b32 s1, 0
	v_lshl_add_u64 v[218:219], v[218:219], 0, s[0:1]
	s_waitcnt vmcnt(25)
	v_lshlrev_b32_e32 v220, 16, v138
	v_and_b32_e32 v221, 0xffff0000, v138
	v_lshlrev_b32_e32 v138, 16, v139
	v_and_b32_e32 v139, 0xffff0000, v139
	v_lshlrev_b32_e32 v222, 16, v140
	v_and_b32_e32 v223, 0xffff0000, v140
	v_lshlrev_b32_e32 v140, 16, v141
	v_and_b32_e32 v141, 0xffff0000, v141
	v_sub_f32_e32 v221, v221, v148
	v_sub_f32_e32 v220, v220, v148
	v_sub_f32_e32 v139, v139, v148
	v_sub_f32_e32 v138, v138, v148
	v_pk_mul_f32 v[138:139], v[148:149], v[138:139] op_sel:[1,0]
	v_pk_mul_f32 v[220:221], v[148:149], v[220:221] op_sel:[1,0]
	v_sub_f32_e32 v223, v223, v148
	v_sub_f32_e32 v222, v222, v148
	v_sub_f32_e32 v141, v141, v148
	v_sub_f32_e32 v140, v140, v148
	v_pk_fma_f32 v[220:221], v[166:167], v[220:221], v[170:171]
	v_pk_fma_f32 v[138:139], v[168:169], v[138:139], v[172:173]
	v_pk_mul_f32 v[140:141], v[148:149], v[140:141] op_sel:[1,0]
	v_pk_mul_f32 v[222:223], v[148:149], v[222:223] op_sel:[1,0]
	v_pk_mul_f32 v[56:57], v[176:177], v[56:57]
	v_pk_mul_f32 v[54:55], v[174:175], v[54:55]
	v_pk_fma_f32 v[222:223], v[154:155], v[222:223], v[162:163]
	v_pk_fma_f32 v[140:141], v[156:157], v[140:141], v[164:165]
	v_pk_fma_f32 v[56:57], v[138:139], s[56:57], v[56:57] op_sel_hi:[1,0,1]
	v_pk_fma_f32 v[54:55], v[220:221], s[56:57], v[54:55] op_sel_hi:[1,0,1]
	v_pk_mul_f32 v[52:53], v[160:161], v[52:53]
	v_pk_mul_f32 v[50:51], v[158:159], v[50:51]
	v_pk_fma_f32 v[52:53], v[140:141], s[56:57], v[52:53] op_sel_hi:[1,0,1]
	v_pk_fma_f32 v[50:51], v[222:223], s[56:57], v[50:51] op_sel_hi:[1,0,1]
	v_cvt_pk_bf16_f32 v54, v54, v55
	v_cvt_pk_bf16_f32 v55, v56, v57
	v_cvt_pk_bf16_f32 v56, v50, v51
	v_cvt_pk_bf16_f32 v57, v52, v53
	global_store_dwordx4 v[218:219], v[54:57], off
	s_nop 0
	global_load_dwordx2 v[54:55], v[214:215], off offset:1152
	global_load_dwordx4 v[50:53], v[218:219], off offset:256
	v_lshl_add_u64 v[218:219], v[218:219], 0, s[0:1]
	s_waitcnt vmcnt(26)
	v_lshlrev_b32_e32 v220, 16, v142
	v_and_b32_e32 v221, 0xffff0000, v142
	v_lshlrev_b32_e32 v142, 16, v143
	v_and_b32_e32 v143, 0xffff0000, v143
	v_lshlrev_b32_e32 v222, 16, v144
	v_and_b32_e32 v223, 0xffff0000, v144
	v_lshlrev_b32_e32 v144, 16, v145
	v_and_b32_e32 v145, 0xffff0000, v145
	v_sub_f32_e32 v221, v221, v150
	v_sub_f32_e32 v220, v220, v150
	v_sub_f32_e32 v143, v143, v150
	v_sub_f32_e32 v142, v142, v150
	v_pk_mul_f32 v[142:143], v[150:151], v[142:143] op_sel:[1,0]
	v_pk_mul_f32 v[220:221], v[150:151], v[220:221] op_sel:[1,0]
	v_sub_f32_e32 v223, v223, v150
	v_sub_f32_e32 v222, v222, v150
	v_sub_f32_e32 v145, v145, v150
	v_sub_f32_e32 v144, v144, v150
	v_pk_fma_f32 v[220:221], v[166:167], v[220:221], v[170:171]
	v_pk_fma_f32 v[142:143], v[168:169], v[142:143], v[172:173]
	v_pk_mul_f32 v[144:145], v[150:151], v[144:145] op_sel:[1,0]
	v_pk_mul_f32 v[222:223], v[150:151], v[222:223] op_sel:[1,0]
	v_pk_mul_f32 v[48:49], v[176:177], v[48:49]
	v_pk_mul_f32 v[46:47], v[174:175], v[46:47]
	v_pk_fma_f32 v[222:223], v[154:155], v[222:223], v[162:163]
	v_pk_fma_f32 v[144:145], v[156:157], v[144:145], v[164:165]
	v_pk_fma_f32 v[48:49], v[142:143], s[56:57], v[48:49] op_sel_hi:[1,0,1]
	v_pk_fma_f32 v[46:47], v[220:221], s[56:57], v[46:47] op_sel_hi:[1,0,1]
	v_pk_mul_f32 v[44:45], v[160:161], v[44:45]
	v_pk_mul_f32 v[42:43], v[158:159], v[42:43]
	v_pk_fma_f32 v[44:45], v[144:145], s[56:57], v[44:45] op_sel_hi:[1,0,1]
	v_pk_fma_f32 v[42:43], v[222:223], s[56:57], v[42:43] op_sel_hi:[1,0,1]
	v_cvt_pk_bf16_f32 v46, v46, v47
	v_cvt_pk_bf16_f32 v47, v48, v49
	v_cvt_pk_bf16_f32 v48, v42, v43
	v_cvt_pk_bf16_f32 v49, v44, v45
	global_store_dwordx4 v[218:219], v[46:49], off
	s_nop 0
	global_load_dwordx2 v[46:47], v[214:215], off offset:1280
	global_load_dwordx4 v[42:45], v[218:219], off offset:256
	v_lshl_add_u64 v[218:219], v[218:219], 0, s[0:1]
	s_waitcnt vmcnt(9)
	v_lshlrev_b32_e32 v220, 16, v130
	v_and_b32_e32 v221, 0xffff0000, v130
	v_lshlrev_b32_e32 v130, 16, v131
	v_and_b32_e32 v131, 0xffff0000, v131
	v_lshlrev_b32_e32 v222, 16, v132
	v_and_b32_e32 v223, 0xffff0000, v132
	v_lshlrev_b32_e32 v132, 16, v133
	v_and_b32_e32 v133, 0xffff0000, v133
	v_sub_f32_e32 v221, v221, v248
	v_sub_f32_e32 v220, v220, v248
	v_sub_f32_e32 v131, v131, v248
	v_sub_f32_e32 v130, v130, v248
	v_pk_mul_f32 v[130:131], v[248:249], v[130:131] op_sel:[1,0]
	v_pk_mul_f32 v[220:221], v[248:249], v[220:221] op_sel:[1,0]
	v_sub_f32_e32 v223, v223, v248
	v_sub_f32_e32 v222, v222, v248
	v_sub_f32_e32 v133, v133, v248
	v_sub_f32_e32 v132, v132, v248
	v_pk_fma_f32 v[220:221], v[166:167], v[220:221], v[170:171]
	v_pk_fma_f32 v[130:131], v[168:169], v[130:131], v[172:173]
	v_pk_mul_f32 v[132:133], v[248:249], v[132:133] op_sel:[1,0]
	v_pk_mul_f32 v[222:223], v[248:249], v[222:223] op_sel:[1,0]
	v_pk_mul_f32 v[40:41], v[176:177], v[40:41]
	v_pk_mul_f32 v[38:39], v[174:175], v[38:39]
	v_pk_fma_f32 v[222:223], v[154:155], v[222:223], v[162:163]
	v_pk_fma_f32 v[132:133], v[156:157], v[132:133], v[164:165]
	v_pk_fma_f32 v[40:41], v[130:131], s[56:57], v[40:41] op_sel_hi:[1,0,1]
	v_pk_fma_f32 v[38:39], v[220:221], s[56:57], v[38:39] op_sel_hi:[1,0,1]
	v_pk_mul_f32 v[36:37], v[160:161], v[36:37]
	v_pk_mul_f32 v[34:35], v[158:159], v[34:35]
	v_pk_fma_f32 v[36:37], v[132:133], s[56:57], v[36:37] op_sel_hi:[1,0,1]
	v_pk_fma_f32 v[34:35], v[222:223], s[56:57], v[34:35] op_sel_hi:[1,0,1]
	v_cvt_pk_bf16_f32 v38, v38, v39
	v_cvt_pk_bf16_f32 v39, v40, v41
	v_cvt_pk_bf16_f32 v40, v34, v35
	v_cvt_pk_bf16_f32 v41, v36, v37
	global_store_dwordx4 v[218:219], v[38:41], off
	s_nop 0
	global_load_dwordx2 v[38:39], v[214:215], off offset:1408
	global_load_dwordx4 v[34:37], v[218:219], off offset:256
	s_mov_b32 s0, 0xfffa8000
	s_mov_b32 s1, 0xffffffff
	v_lshl_add_u64 v[216:217], v[216:217], 0, s[0:1]
	s_waitcnt vmcnt(17)
	v_lshlrev_b32_e32 v220, 16, v178
	v_and_b32_e32 v221, 0xffff0000, v178
	v_lshlrev_b32_e32 v178, 16, v179
	v_and_b32_e32 v179, 0xffff0000, v179
	v_lshlrev_b32_e32 v222, 16, v180
	v_and_b32_e32 v223, 0xffff0000, v180
	v_lshlrev_b32_e32 v180, 16, v181
	v_and_b32_e32 v181, 0xffff0000, v181
	v_sub_f32_e32 v221, v221, v194
	v_sub_f32_e32 v220, v220, v194
	v_sub_f32_e32 v179, v179, v194
	v_sub_f32_e32 v178, v178, v194
	v_pk_mul_f32 v[178:179], v[194:195], v[178:179] op_sel:[1,0]
	v_pk_mul_f32 v[220:221], v[194:195], v[220:221] op_sel:[1,0]
	v_sub_f32_e32 v223, v223, v194
	v_sub_f32_e32 v222, v222, v194
	v_sub_f32_e32 v181, v181, v194
	v_sub_f32_e32 v180, v180, v194
	v_pk_fma_f32 v[220:221], v[118:119], v[220:221], v[110:111]
	v_pk_fma_f32 v[178:179], v[120:121], v[178:179], v[112:113]
	v_pk_mul_f32 v[180:181], v[194:195], v[180:181] op_sel:[1,0]
	v_pk_mul_f32 v[222:223], v[194:195], v[222:223] op_sel:[1,0]
	v_pk_mul_f32 v[96:97], v[128:129], v[96:97]
	v_pk_mul_f32 v[94:95], v[126:127], v[94:95]
	v_pk_fma_f32 v[222:223], v[114:115], v[222:223], v[106:107]
	v_pk_fma_f32 v[180:181], v[116:117], v[180:181], v[108:109]
	v_pk_fma_f32 v[96:97], v[178:179], s[56:57], v[96:97] op_sel_hi:[1,0,1]
	v_pk_fma_f32 v[94:95], v[220:221], s[56:57], v[94:95] op_sel_hi:[1,0,1]
	v_pk_mul_f32 v[92:93], v[124:125], v[92:93]
	v_pk_mul_f32 v[90:91], v[122:123], v[90:91]
	v_pk_fma_f32 v[92:93], v[180:181], s[56:57], v[92:93] op_sel_hi:[1,0,1]
	v_pk_fma_f32 v[90:91], v[222:223], s[56:57], v[90:91] op_sel_hi:[1,0,1]
	v_cvt_pk_bf16_f32 v94, v94, v95
	v_cvt_pk_bf16_f32 v95, v96, v97
	v_cvt_pk_bf16_f32 v96, v90, v91
	v_cvt_pk_bf16_f32 v97, v92, v93
	global_store_dwordx4 v[216:217], v[94:97], off offset:256
	s_mov_b32 s0, 0x8000
	s_mov_b32 s1, 0
	v_lshl_add_u64 v[216:217], v[216:217], 0, s[0:1]
	s_waitcnt vmcnt(18)
	v_lshlrev_b32_e32 v220, 16, v182
	v_and_b32_e32 v221, 0xffff0000, v182
	v_lshlrev_b32_e32 v182, 16, v183
	v_and_b32_e32 v183, 0xffff0000, v183
	v_lshlrev_b32_e32 v222, 16, v184
	v_and_b32_e32 v223, 0xffff0000, v184
	v_lshlrev_b32_e32 v184, 16, v185
	v_and_b32_e32 v185, 0xffff0000, v185
	v_sub_f32_e32 v221, v221, v196
	v_sub_f32_e32 v220, v220, v196
	v_sub_f32_e32 v183, v183, v196
	v_sub_f32_e32 v182, v182, v196
	v_pk_mul_f32 v[182:183], v[196:197], v[182:183] op_sel:[1,0]
	v_pk_mul_f32 v[220:221], v[196:197], v[220:221] op_sel:[1,0]
	v_sub_f32_e32 v223, v223, v196
	v_sub_f32_e32 v222, v222, v196
	v_sub_f32_e32 v185, v185, v196
	v_sub_f32_e32 v184, v184, v196
	v_pk_fma_f32 v[220:221], v[118:119], v[220:221], v[110:111]
	v_pk_fma_f32 v[182:183], v[120:121], v[182:183], v[112:113]
	v_pk_mul_f32 v[184:185], v[196:197], v[184:185] op_sel:[1,0]
	v_pk_mul_f32 v[222:223], v[196:197], v[222:223] op_sel:[1,0]
	v_pk_mul_f32 v[88:89], v[128:129], v[88:89]
	v_pk_mul_f32 v[86:87], v[126:127], v[86:87]
	v_pk_fma_f32 v[222:223], v[114:115], v[222:223], v[106:107]
	v_pk_fma_f32 v[184:185], v[116:117], v[184:185], v[108:109]
	v_pk_fma_f32 v[88:89], v[182:183], s[56:57], v[88:89] op_sel_hi:[1,0,1]
	v_pk_fma_f32 v[86:87], v[220:221], s[56:57], v[86:87] op_sel_hi:[1,0,1]
	v_pk_mul_f32 v[84:85], v[124:125], v[84:85]
	v_pk_mul_f32 v[82:83], v[122:123], v[82:83]
	v_pk_fma_f32 v[84:85], v[184:185], s[56:57], v[84:85] op_sel_hi:[1,0,1]
	v_pk_fma_f32 v[82:83], v[222:223], s[56:57], v[82:83] op_sel_hi:[1,0,1]
	v_cvt_pk_bf16_f32 v86, v86, v87
	v_cvt_pk_bf16_f32 v87, v88, v89
	v_cvt_pk_bf16_f32 v88, v82, v83
	v_cvt_pk_bf16_f32 v89, v84, v85
	global_store_dwordx4 v[216:217], v[86:89], off offset:256
	v_lshl_add_u64 v[216:217], v[216:217], 0, s[0:1]
	s_waitcnt vmcnt(19)
	v_lshlrev_b32_e32 v220, 16, v186
	v_and_b32_e32 v221, 0xffff0000, v186
	v_lshlrev_b32_e32 v186, 16, v187
	v_and_b32_e32 v187, 0xffff0000, v187
	v_lshlrev_b32_e32 v222, 16, v188
	v_and_b32_e32 v223, 0xffff0000, v188
	v_lshlrev_b32_e32 v188, 16, v189
	v_and_b32_e32 v189, 0xffff0000, v189
	v_sub_f32_e32 v221, v221, v232
	v_sub_f32_e32 v220, v220, v232
	v_sub_f32_e32 v187, v187, v232
	v_sub_f32_e32 v186, v186, v232
	v_pk_mul_f32 v[186:187], v[232:233], v[186:187] op_sel:[1,0]
	v_pk_mul_f32 v[220:221], v[232:233], v[220:221] op_sel:[1,0]
	v_sub_f32_e32 v223, v223, v232
	v_sub_f32_e32 v222, v222, v232
	v_sub_f32_e32 v189, v189, v232
	v_sub_f32_e32 v188, v188, v232
	v_pk_fma_f32 v[220:221], v[118:119], v[220:221], v[110:111]
	v_pk_fma_f32 v[186:187], v[120:121], v[186:187], v[112:113]
	v_pk_mul_f32 v[188:189], v[232:233], v[188:189] op_sel:[1,0]
	v_pk_mul_f32 v[222:223], v[232:233], v[222:223] op_sel:[1,0]
	v_pk_mul_f32 v[80:81], v[128:129], v[80:81]
	v_pk_mul_f32 v[78:79], v[126:127], v[78:79]
	v_pk_fma_f32 v[222:223], v[114:115], v[222:223], v[106:107]
	v_pk_fma_f32 v[188:189], v[116:117], v[188:189], v[108:109]
	v_pk_fma_f32 v[80:81], v[186:187], s[56:57], v[80:81] op_sel_hi:[1,0,1]
	v_pk_fma_f32 v[78:79], v[220:221], s[56:57], v[78:79] op_sel_hi:[1,0,1]
	v_pk_mul_f32 v[76:77], v[124:125], v[76:77]
	v_pk_mul_f32 v[74:75], v[122:123], v[74:75]
	v_pk_fma_f32 v[76:77], v[188:189], s[56:57], v[76:77] op_sel_hi:[1,0,1]
	v_pk_fma_f32 v[74:75], v[222:223], s[56:57], v[74:75] op_sel_hi:[1,0,1]
	v_cvt_pk_bf16_f32 v78, v78, v79
	v_cvt_pk_bf16_f32 v79, v80, v81
	v_cvt_pk_bf16_f32 v80, v74, v75
	v_cvt_pk_bf16_f32 v81, v76, v77
	global_store_dwordx4 v[216:217], v[78:81], off offset:256
	v_lshl_add_u64 v[216:217], v[216:217], 0, s[0:1]
	s_waitcnt vmcnt(17)
	v_lshlrev_b32_e32 v220, 16, v98
	v_and_b32_e32 v221, 0xffff0000, v98
	v_lshlrev_b32_e32 v98, 16, v99
	v_and_b32_e32 v99, 0xffff0000, v99
	v_lshlrev_b32_e32 v222, 16, v100
	v_and_b32_e32 v223, 0xffff0000, v100
	v_lshlrev_b32_e32 v100, 16, v101
	v_and_b32_e32 v101, 0xffff0000, v101
	v_sub_f32_e32 v221, v221, v102
	v_sub_f32_e32 v220, v220, v102
	v_sub_f32_e32 v99, v99, v102
	v_sub_f32_e32 v98, v98, v102
	v_pk_mul_f32 v[98:99], v[102:103], v[98:99] op_sel:[1,0]
	v_pk_mul_f32 v[220:221], v[102:103], v[220:221] op_sel:[1,0]
	v_sub_f32_e32 v223, v223, v102
	v_sub_f32_e32 v222, v222, v102
	v_sub_f32_e32 v101, v101, v102
	v_sub_f32_e32 v100, v100, v102
	v_pk_fma_f32 v[220:221], v[118:119], v[220:221], v[110:111]
	v_pk_fma_f32 v[98:99], v[120:121], v[98:99], v[112:113]
	v_pk_mul_f32 v[100:101], v[102:103], v[100:101] op_sel:[1,0]
	v_pk_mul_f32 v[222:223], v[102:103], v[222:223] op_sel:[1,0]
	v_pk_mul_f32 v[72:73], v[128:129], v[72:73]
	v_pk_mul_f32 v[70:71], v[126:127], v[70:71]
	v_pk_fma_f32 v[222:223], v[114:115], v[222:223], v[106:107]
	v_pk_fma_f32 v[100:101], v[116:117], v[100:101], v[108:109]
	v_pk_fma_f32 v[72:73], v[98:99], s[56:57], v[72:73] op_sel_hi:[1,0,1]
	v_pk_fma_f32 v[70:71], v[220:221], s[56:57], v[70:71] op_sel_hi:[1,0,1]
	v_pk_mul_f32 v[68:69], v[124:125], v[68:69]
	v_pk_mul_f32 v[66:67], v[122:123], v[66:67]
	v_pk_fma_f32 v[68:69], v[100:101], s[56:57], v[68:69] op_sel_hi:[1,0,1]
	v_pk_fma_f32 v[66:67], v[222:223], s[56:57], v[66:67] op_sel_hi:[1,0,1]
	v_cvt_pk_bf16_f32 v70, v70, v71
	v_cvt_pk_bf16_f32 v71, v72, v73
	v_cvt_pk_bf16_f32 v72, v66, v67
	v_cvt_pk_bf16_f32 v73, v68, v69
	global_store_dwordx4 v[216:217], v[70:73], off offset:256
	s_mov_b32 s0, 0x28000
	s_mov_b32 s1, 0
	v_lshl_add_u64 v[216:217], v[216:217], 0, s[0:1]
	s_waitcnt vmcnt(13)
	v_lshlrev_b32_e32 v220, 16, v58
	v_and_b32_e32 v221, 0xffff0000, v58
	v_lshlrev_b32_e32 v58, 16, v59
	v_and_b32_e32 v59, 0xffff0000, v59
	v_lshlrev_b32_e32 v222, 16, v60
	v_and_b32_e32 v223, 0xffff0000, v60
	v_lshlrev_b32_e32 v60, 16, v61
	v_and_b32_e32 v61, 0xffff0000, v61
	v_sub_f32_e32 v221, v221, v62
	v_sub_f32_e32 v220, v220, v62
	v_sub_f32_e32 v59, v59, v62
	v_sub_f32_e32 v58, v58, v62
	v_pk_mul_f32 v[58:59], v[62:63], v[58:59] op_sel:[1,0]
	v_pk_mul_f32 v[220:221], v[62:63], v[220:221] op_sel:[1,0]
	v_sub_f32_e32 v223, v223, v62
	v_sub_f32_e32 v222, v222, v62
	v_sub_f32_e32 v61, v61, v62
	v_sub_f32_e32 v60, v60, v62
	v_pk_fma_f32 v[220:221], v[118:119], v[220:221], v[110:111]
	v_pk_fma_f32 v[58:59], v[120:121], v[58:59], v[112:113]
	v_pk_mul_f32 v[60:61], v[62:63], v[60:61] op_sel:[1,0]
	v_pk_mul_f32 v[222:223], v[62:63], v[222:223] op_sel:[1,0]
	v_pk_mul_f32 v[32:33], v[128:129], v[32:33]
	v_pk_mul_f32 v[30:31], v[126:127], v[30:31]
	v_pk_fma_f32 v[222:223], v[114:115], v[222:223], v[106:107]
	v_pk_fma_f32 v[60:61], v[116:117], v[60:61], v[108:109]
	v_pk_fma_f32 v[32:33], v[58:59], s[56:57], v[32:33] op_sel_hi:[1,0,1]
	v_pk_fma_f32 v[30:31], v[220:221], s[56:57], v[30:31] op_sel_hi:[1,0,1]
	v_pk_mul_f32 v[28:29], v[124:125], v[28:29]
	v_pk_mul_f32 v[26:27], v[122:123], v[26:27]
	v_pk_fma_f32 v[28:29], v[60:61], s[56:57], v[28:29] op_sel_hi:[1,0,1]
	v_pk_fma_f32 v[26:27], v[222:223], s[56:57], v[26:27] op_sel_hi:[1,0,1]
	v_cvt_pk_bf16_f32 v30, v30, v31
	v_cvt_pk_bf16_f32 v31, v32, v33
	v_cvt_pk_bf16_f32 v32, v26, v27
	v_cvt_pk_bf16_f32 v33, v28, v29
	global_store_dwordx4 v[216:217], v[30:33], off offset:256
	s_mov_b32 s0, 0x8000
	s_mov_b32 s1, 0
	v_lshl_add_u64 v[216:217], v[216:217], 0, s[0:1]
	s_waitcnt vmcnt(11)
	v_lshlrev_b32_e32 v220, 16, v50
	v_and_b32_e32 v221, 0xffff0000, v50
	v_lshlrev_b32_e32 v50, 16, v51
	v_and_b32_e32 v51, 0xffff0000, v51
	v_lshlrev_b32_e32 v222, 16, v52
	v_and_b32_e32 v223, 0xffff0000, v52
	v_lshlrev_b32_e32 v52, 16, v53
	v_and_b32_e32 v53, 0xffff0000, v53
	v_sub_f32_e32 v221, v221, v54
	v_sub_f32_e32 v220, v220, v54
	v_sub_f32_e32 v51, v51, v54
	v_sub_f32_e32 v50, v50, v54
	v_pk_mul_f32 v[50:51], v[54:55], v[50:51] op_sel:[1,0]
	v_pk_mul_f32 v[220:221], v[54:55], v[220:221] op_sel:[1,0]
	v_sub_f32_e32 v223, v223, v54
	v_sub_f32_e32 v222, v222, v54
	v_sub_f32_e32 v53, v53, v54
	v_sub_f32_e32 v52, v52, v54
	v_pk_fma_f32 v[220:221], v[118:119], v[220:221], v[110:111]
	v_pk_fma_f32 v[50:51], v[120:121], v[50:51], v[112:113]
	v_pk_mul_f32 v[52:53], v[54:55], v[52:53] op_sel:[1,0]
	v_pk_mul_f32 v[222:223], v[54:55], v[222:223] op_sel:[1,0]
	v_pk_mul_f32 v[24:25], v[128:129], v[24:25]
	v_pk_mul_f32 v[22:23], v[126:127], v[22:23]
	v_pk_fma_f32 v[222:223], v[114:115], v[222:223], v[106:107]
	v_pk_fma_f32 v[52:53], v[116:117], v[52:53], v[108:109]
	v_pk_fma_f32 v[24:25], v[50:51], s[56:57], v[24:25] op_sel_hi:[1,0,1]
	v_pk_fma_f32 v[22:23], v[220:221], s[56:57], v[22:23] op_sel_hi:[1,0,1]
	v_pk_mul_f32 v[20:21], v[124:125], v[20:21]
	v_pk_mul_f32 v[18:19], v[122:123], v[18:19]
	v_pk_fma_f32 v[20:21], v[52:53], s[56:57], v[20:21] op_sel_hi:[1,0,1]
	v_pk_fma_f32 v[18:19], v[222:223], s[56:57], v[18:19] op_sel_hi:[1,0,1]
	v_cvt_pk_bf16_f32 v22, v22, v23
	v_cvt_pk_bf16_f32 v23, v24, v25
	v_cvt_pk_bf16_f32 v24, v18, v19
	v_cvt_pk_bf16_f32 v25, v20, v21
	global_store_dwordx4 v[216:217], v[22:25], off offset:256
	v_lshl_add_u64 v[216:217], v[216:217], 0, s[0:1]
	s_waitcnt vmcnt(9)
	v_lshlrev_b32_e32 v220, 16, v42
	v_and_b32_e32 v221, 0xffff0000, v42
	v_lshlrev_b32_e32 v42, 16, v43
	v_and_b32_e32 v43, 0xffff0000, v43
	v_lshlrev_b32_e32 v222, 16, v44
	v_and_b32_e32 v223, 0xffff0000, v44
	v_lshlrev_b32_e32 v44, 16, v45
	v_and_b32_e32 v45, 0xffff0000, v45
	v_sub_f32_e32 v221, v221, v46
	v_sub_f32_e32 v220, v220, v46
	v_sub_f32_e32 v43, v43, v46
	v_sub_f32_e32 v42, v42, v46
	v_pk_mul_f32 v[42:43], v[46:47], v[42:43] op_sel:[1,0]
	v_pk_mul_f32 v[220:221], v[46:47], v[220:221] op_sel:[1,0]
	v_sub_f32_e32 v223, v223, v46
	v_sub_f32_e32 v222, v222, v46
	v_sub_f32_e32 v45, v45, v46
	v_sub_f32_e32 v44, v44, v46
	v_pk_fma_f32 v[220:221], v[118:119], v[220:221], v[110:111]
	v_pk_fma_f32 v[42:43], v[120:121], v[42:43], v[112:113]
	v_pk_mul_f32 v[44:45], v[46:47], v[44:45] op_sel:[1,0]
	v_pk_mul_f32 v[222:223], v[46:47], v[222:223] op_sel:[1,0]
	v_pk_mul_f32 v[16:17], v[128:129], v[16:17]
	v_pk_mul_f32 v[14:15], v[126:127], v[14:15]
	v_pk_fma_f32 v[222:223], v[114:115], v[222:223], v[106:107]
	v_pk_fma_f32 v[44:45], v[116:117], v[44:45], v[108:109]
	v_pk_fma_f32 v[16:17], v[42:43], s[56:57], v[16:17] op_sel_hi:[1,0,1]
	v_pk_fma_f32 v[14:15], v[220:221], s[56:57], v[14:15] op_sel_hi:[1,0,1]
	v_pk_mul_f32 v[12:13], v[124:125], v[12:13]
	v_pk_mul_f32 v[10:11], v[122:123], v[10:11]
	v_pk_fma_f32 v[12:13], v[44:45], s[56:57], v[12:13] op_sel_hi:[1,0,1]
	v_pk_fma_f32 v[10:11], v[222:223], s[56:57], v[10:11] op_sel_hi:[1,0,1]
	v_cvt_pk_bf16_f32 v14, v14, v15
	v_cvt_pk_bf16_f32 v15, v16, v17
	v_cvt_pk_bf16_f32 v16, v10, v11
	v_cvt_pk_bf16_f32 v17, v12, v13
	global_store_dwordx4 v[216:217], v[14:17], off offset:256
	v_lshl_add_u64 v[216:217], v[216:217], 0, s[0:1]
	s_waitcnt vmcnt(7)
	v_lshlrev_b32_e32 v220, 16, v34
	v_and_b32_e32 v221, 0xffff0000, v34
	v_lshlrev_b32_e32 v34, 16, v35
	v_and_b32_e32 v35, 0xffff0000, v35
	v_lshlrev_b32_e32 v222, 16, v36
	v_and_b32_e32 v223, 0xffff0000, v36
	v_lshlrev_b32_e32 v36, 16, v37
	v_and_b32_e32 v37, 0xffff0000, v37
	v_sub_f32_e32 v221, v221, v38
	v_sub_f32_e32 v220, v220, v38
	v_sub_f32_e32 v35, v35, v38
	v_sub_f32_e32 v34, v34, v38
	v_pk_mul_f32 v[34:35], v[38:39], v[34:35] op_sel:[1,0]
	v_pk_mul_f32 v[220:221], v[38:39], v[220:221] op_sel:[1,0]
	v_sub_f32_e32 v223, v223, v38
	v_sub_f32_e32 v222, v222, v38
	v_sub_f32_e32 v37, v37, v38
	v_sub_f32_e32 v36, v36, v38
	v_pk_fma_f32 v[220:221], v[118:119], v[220:221], v[110:111]
	v_pk_fma_f32 v[34:35], v[120:121], v[34:35], v[112:113]
	v_pk_mul_f32 v[36:37], v[38:39], v[36:37] op_sel:[1,0]
	v_pk_mul_f32 v[222:223], v[38:39], v[222:223] op_sel:[1,0]
	v_pk_mul_f32 v[8:9], v[128:129], v[8:9]
	v_pk_mul_f32 v[6:7], v[126:127], v[6:7]
	v_pk_fma_f32 v[222:223], v[114:115], v[222:223], v[106:107]
	v_pk_fma_f32 v[36:37], v[116:117], v[36:37], v[108:109]
	v_pk_fma_f32 v[8:9], v[34:35], s[56:57], v[8:9] op_sel_hi:[1,0,1]
	v_pk_fma_f32 v[6:7], v[220:221], s[56:57], v[6:7] op_sel_hi:[1,0,1]
	v_pk_mul_f32 v[4:5], v[124:125], v[4:5]
	v_pk_mul_f32 v[2:3], v[122:123], v[2:3]
	v_pk_fma_f32 v[4:5], v[36:37], s[56:57], v[4:5] op_sel_hi:[1,0,1]
	v_pk_fma_f32 v[2:3], v[222:223], s[56:57], v[2:3] op_sel_hi:[1,0,1]
	v_cvt_pk_bf16_f32 v6, v6, v7
	v_cvt_pk_bf16_f32 v7, v8, v9
	v_cvt_pk_bf16_f32 v8, v2, v3
	v_cvt_pk_bf16_f32 v9, v4, v5
	global_store_dwordx4 v[216:217], v[6:9], off offset:256
	s_mov_b64 s[14:15], 0
